# MoBA inner loop: waves 4-7 start each 64-key step 384 clocks late (s_sleep 6) to stagger MFMA and softmax phases of SIMD partners
# baseline (speedup 1.0000x reference)
; #define LAS __attribute__((address_space(3)))
; #define DMA_PAIR(u_, pb_) do { DMA16(kgu + (size_t)(2 * (u_)) * 4096 + so, (pb_)); DMA16(kgu + (size_t)(2 * (u_) + 1) * 4096 + so, (pb_) + 8192); DMA16(vgu + (size_t)(2 * (u_)) * 4096 + so, 32768 + (pb_)); DMA16(vgu + (size_t)(2 * (u_) + 1) * 4096 + so, 32768 + (pb_) + 8192); } while (0)
; template <int l> __device__ __forceinline__ void layer_body(const Args& args, LAS unsigned char* lds, const XcdBarrier& bar) {
;     ...
;                     for (int u = 0; u <= umax; ++u) {
;                         if (u < umax) DMA_PAIR(u + 1, ((u + 1) & 1) * 16384);
;                         if (2 * u <= j) {
;                             const int ta = 2 * u; const bool hasb = (ta + 1 <= j);
;                             const LAS bf16* kl = (const LAS bf16*)(lds + (u & 1) * 16384) + (hh * 32 + pr) * 8; const LAS bf16* vl = (const LAS bf16*)(lds + 32768 + (u & 1) * 16384) + (hh * 128 + r) * 8;
.LBB0_1510:
	s_bitcmp1_b32 s33, 12
	s_cbranch_scc0 .Lmskew
	s_sleep 6
